# fold 0+x adds in NSA softmax sums (3 sites), on v49
# baseline (speedup 1.0000x reference)
; template <int MODE>
; __device__ __forceinline__ void nsa_soft(f32x4 (&st)[4], const float (&Bl)[16], float cl, bool fast, int keybase, int t, bool sel, float& m2, float& l, f32x4 (&o)[4], float lfin, LAS float* imp, int lane) {
;     ...
;         float mloc = fmaxf(fmaxf(fmaxf(st[0][0], st[0][1]), fmaxf(st[0][2], st[0][3])), fmaxf(fmaxf(st[1][0], st[1][1]), fmaxf(st[1][2], st[1][3])));
;         mloc = fmaxf(mloc, fmaxf(fmaxf(fmaxf(st[2][0], st[2][1]), fmaxf(st[2][2], st[2][3])), fmaxf(fmaxf(st[3][0], st[3][1]), fmaxf(st[3][2], st[3][3]))));
;         mloc = xrow16_max(mloc);
;         const float mnew = fmaxf(m2, mloc + cl); const float alpha = __builtin_amdgcn_exp2f(m2 - mnew); m2 = mnew;
;         const float sh = cl - mnew;
;         float ps = 0.f;
; #pragma unroll
;         for (int tau = 0; tau < 4; ++tau)
; #pragma unroll
;             for (int r = 0; r < 4; ++r) { const float p = __builtin_amdgcn_exp2f(st[tau][r] + sh); st[tau][r] = p; ps += p; }
;         l = l * alpha + ps;
;         if (MODE != 0) {
; #pragma unroll
;             for (int dt = 0; dt < 4; ++dt) o[dt] = o[dt] * alpha;
;         }
;     }
; }
; template <int MODE> ...
;     const int kg = lane >> 4;
;     f32x4 st[2][4];
;     { const int rho = lane & 15, dof = kg * 8;
; #pragma unroll
;       for (int tau = 0; tau < 4; ++tau) { const LAS bf16* rp = kt + (16 * tau + rho) * KT_LD + dof;
;           const bf16x8 k0 = *(const LAS bf16x8*)(rp), k1 = *(const LAS bf16x8*)(rp + 32);
; #pragma unroll
;           for (int s = 0; s < 2; ++s) { st[s][tau] = (f32x4){0.f, 0.f, 0.f, 0.f}; st[s][tau] = mfma16(k0, qf[s][0], st[s][tau]); st[s][tau] = mfma16(k1, qf[s][1], st[s][tau]); } } }
; #pragma unroll
;     for (int s = 0; s < 2; ++s) nsa_soft<MODE>(st[s], Bl, cl[s], fast, keybase, t[s], sel[s], m2[s], l[s], o[s], lfin[s], imp + s * 1024, lane);
;     if (MODE != 0) {
;         bf16x8 pb[2][2];
; #pragma unroll
;         for (int s = 0; s < 2; ++s) { pb[s][0] = pack_p(st[s][0], st[s][1]); pb[s][1] = pack_p(st[s][2], st[s][3]); }
; #pragma unroll
;         for (int dt = 0; dt < 4; ++dt) { const LAS bf16* vp = vt + (dt * 16 + (lane & 15)) * KT_LD + 8 * kg;
;             const bf16x8 v0 = *(const LAS bf16x8*)(vp), v1 = *(const LAS bf16x8*)(vp + 32);
; #pragma unroll
;             for (int s = 0; s < 2; ++s) { o[s][dt] = mfma16(v0, pb[s][0], o[s][dt]); o[s][dt] = mfma16(v1, pb[s][1], o[s][dt]); } }
.LBB0_1044:
	v_sub_u32_e32 v64, s20, v162
	v_cvt_f32_i32_e32 v64, v64
	s_xor_b64 s[10:11], s[10:11], -1
	s_and_b64 vcc, s[56:57], s[10:11]
	v_mul_f32_e32 v64, v154, v64
	v_cndmask_b32_e32 v64, v64, v225, vcc
	v_max_f32_e32 v65, v242, v241
	v_add_f32_e32 v65, v64, v65
	v_max_f32_e32 v227, v163, v65
	v_sub_f32_e32 v64, v64, v227
	v_add_f32_e32 v65, v188, v64
	v_exp_f32_e32 v65, v65
	v_add_f32_e32 v66, v189, v64
	v_exp_f32_e32 v66, v66
	v_add_f32_e32 v67, v86, v64
	v_exp_f32_e32 v67, v67
	v_add_f32_e32 v71, v87, v64
	v_exp_f32_e32 v71, v71
	v_add_f32_e32 v73, v84, v64
	v_exp_f32_e32 v73, v73
	v_add_f32_e32 v84, v85, v64
	v_add_f32_e32 v70, v66, v65
	v_exp_f32_e32 v84, v84
	v_add_f32_e32 v82, v82, v64
	v_add_f32_e32 v70, v67, v70
	v_exp_f32_e32 v82, v82
	v_add_f32_e32 v70, v71, v70
	v_add_f32_e32 v70, v73, v70
	v_add_f32_e32 v70, v84, v70
	v_sub_f32_e32 v72, v163, v227
	v_add_f32_e32 v163, v82, v70
	v_add_f32_e32 v70, v83, v64
	v_exp_f32_e32 v83, v70
	v_add_f32_e32 v70, v80, v64
	v_exp_f32_e32 v80, v70
	v_add_f32_e32 v70, v81, v64
	v_exp_f32_e32 v81, v70
	v_add_f32_e32 v70, v78, v64
	v_exp_f32_e32 v78, v70
	v_add_f32_e32 v70, v79, v64
	v_exp_f32_e32 v79, v70
	v_add_f32_e32 v70, v76, v64
	v_exp_f32_e32 v76, v70
	v_add_f32_e32 v70, v77, v64
	v_exp_f32_e32 v77, v70
	v_add_f32_e32 v70, v74, v64
	v_exp_f32_e32 v188, v70
	v_sub_u32_e32 v70, s20, v164
	v_cvt_f32_i32_e32 v70, v70
	v_add_f32_e32 v64, v75, v64
	v_exp_f32_e32 v189, v64
	v_mul_f32_e32 v64, v154, v70
	v_max_f32_e32 v70, v192, v193
	v_max_f32_e32 v74, v68, v69
	v_max_f32_e32 v75, v62, v63
	v_max_f32_e32 v85, v60, v61
	v_max_f32_e32 v86, v58, v59
	v_max3_f32 v86, v56, v57, v86
	v_max3_f32 v70, v194, v195, v70
	v_max3_f32 v74, v190, v191, v74
	v_max3_f32 v75, v75, v85, v86
	v_max3_f32 v70, v70, v74, v75
	v_mov_b32_e32 v74, v70
	s_nop 1
	v_permlane16_swap_b32_e32 v70, v74
	v_max_f32_e32 v70, v70, v74
	v_mov_b32_e32 v74, v70
	s_xor_b64 s[10:11], s[12:13], -1
	s_nop 0
	v_permlane32_swap_b32_e32 v70, v74
	s_and_b64 vcc, s[56:57], s[10:11]
	v_cndmask_b32_e32 v64, v64, v225, vcc
	v_max_f32_e32 v70, v70, v74
	v_add_f32_e32 v70, v64, v70
	v_max_f32_e32 v232, v161, v70
	v_sub_f32_e32 v64, v64, v232
	v_add_f32_e32 v70, v194, v64
	v_exp_f32_e32 v233, v70
	v_add_f32_e32 v70, v195, v64
	v_exp_f32_e32 v195, v70
	v_add_f32_e32 v70, v192, v64
	v_add_f32_e32 v56, v56, v64
	v_exp_f32_e32 v234, v70
	v_add_f32_e32 v70, v193, v64
	v_exp_f32_e32 v244, v56
	v_add_f32_e32 v56, v57, v64
	v_exp_f32_e32 v235, v70
	v_add_f32_e32 v70, v190, v64
	v_add_f32_e32 v68, v68, v64
	v_add_f32_e32 v62, v62, v64
	v_add_f32_e32 v60, v60, v64
	v_exp_f32_e32 v245, v56
	v_add_f32_e32 v56, v58, v64
	v_exp_f32_e32 v236, v70
	v_add_f32_e32 v70, v191, v64
	v_exp_f32_e32 v238, v68
	v_add_f32_e32 v68, v69, v64
	v_exp_f32_e32 v240, v62
	v_add_f32_e32 v62, v63, v64
	v_exp_f32_e32 v242, v60
	v_add_f32_e32 v60, v61, v64
	v_exp_f32_e32 v246, v56
	v_add_f32_e32 v56, v59, v64
	v_exp_f32_e32 v237, v70
	v_exp_f32_e32 v239, v68
	v_exp_f32_e32 v241, v62
	v_exp_f32_e32 v243, v60
	v_exp_f32_e32 v247, v56
	v_cvt_pk_bf16_f32 v68, v65, v66
	v_cvt_pk_bf16_f32 v69, v67, v71
	v_cvt_pk_bf16_f32 v70, v73, v84
	v_cvt_pk_bf16_f32 v71, v82, v83
	v_cvt_pk_bf16_f32 v84, v80, v81
	v_cvt_pk_bf16_f32 v85, v78, v79
	v_cvt_pk_bf16_f32 v86, v76, v77
	v_cvt_pk_bf16_f32 v87, v188, v189
	v_cvt_pk_bf16_f32 v190, v233, v195
	v_cvt_pk_bf16_f32 v191, v234, v235
	v_cvt_pk_bf16_f32 v192, v236, v237
	v_cvt_pk_bf16_f32 v193, v238, v239
	v_cvt_pk_bf16_f32 v228, v240, v241
	v_cvt_pk_bf16_f32 v229, v242, v243
	v_cvt_pk_bf16_f32 v230, v244, v245
	v_cvt_pk_bf16_f32 v231, v246, v247
	ds_read_b128 v[56:59], v165 offset:9216
	v_add_f32_e32 v60, v83, v163
	v_exp_f32_e32 v64, v72
	v_add_f32_e32 v65, v80, v60
	ds_read_b128 v[60:63], v165 offset:9280
	v_add_f32_e32 v65, v81, v65
	v_pk_mul_f32 v[54:55], v[54:55], v[64:65] op_sel_hi:[1,0]
	v_pk_mul_f32 v[52:53], v[52:53], v[64:65] op_sel_hi:[1,0]
	v_sub_f32_e32 v66, v161, v232
	v_exp_f32_e32 v194, v66
	s_waitcnt lgkmcnt(1)
; #define LAS __attribute__((address_space(3)))
; __device__ __forceinline__ f32x4 mfma16(bf16x8 a, bf16x8 b, f32x4 c) { return __builtin_amdgcn_mfma_f32_16x16x32_bf16(a, b, c, 0, 0, 0); }
; template <int MODE>
; __device__ __forceinline__ void nsa_soft(f32x4 (&st)[4], const float (&Bl)[16], float cl, bool fast, int keybase, int t, bool sel, float& m2, float& l, f32x4 (&o)[4], float lfin, LAS float* imp, int lane) {
;     ...
;             for (int r = 0; r < 4; ++r) { const float p = __builtin_amdgcn_exp2f(st[tau][r] + sh); st[tau][r] = p; ps += p; }
;         l = l * alpha + ps;
;         if (MODE != 0) {
; #pragma unroll
;             for (int dt = 0; dt < 4; ++dt) o[dt] = o[dt] * alpha;
;         }
;     }
; }
; template <int MODE> ...
;     const int kg = lane >> 4;
;     f32x4 st[2][4];
;     { const int rho = lane & 15, dof = kg * 8;
; #pragma unroll
;       for (int tau = 0; tau < 4; ++tau) { const LAS bf16* rp = kt + (16 * tau + rho) * KT_LD + dof;
;           const bf16x8 k0 = *(const LAS bf16x8*)(rp), k1 = *(const LAS bf16x8*)(rp + 32);
; #pragma unroll
;           for (int s = 0; s < 2; ++s) { st[s][tau] = (f32x4){0.f, 0.f, 0.f, 0.f}; st[s][tau] = mfma16(k0, qf[s][0], st[s][tau]); st[s][tau] = mfma16(k1, qf[s][1], st[s][tau]); } } }
; #pragma unroll
;     for (int s = 0; s < 2; ++s) nsa_soft<MODE>(st[s], Bl, cl[s], fast, keybase, t[s], sel[s], m2[s], l[s], o[s], lfin[s], imp + s * 1024, lane);
;     if (MODE != 0) {
;         bf16x8 pb[2][2];
; #pragma unroll
;         for (int s = 0; s < 2; ++s) { pb[s][0] = pack_p(st[s][0], st[s][1]); pb[s][1] = pack_p(st[s][2], st[s][3]); }
; #pragma unroll
;         for (int dt = 0; dt < 4; ++dt) { const LAS bf16* vp = vt + (dt * 16 + (lane & 15)) * KT_LD + 8 * kg;
;             const bf16x8 v0 = *(const LAS bf16x8*)(vp), v1 = *(const LAS bf16x8*)(vp + 32);
; #pragma unroll
;             for (int s = 0; s < 2; ++s) { o[s][dt] = mfma16(v0, pb[s][0], o[s][dt]); o[s][dt] = mfma16(v1, pb[s][1], o[s][dt]); } }
	v_mfma_f32_16x16x32_bf16 v[52:55], v[56:59], v[68:71], v[52:55]
	v_add_f32_e32 v65, v78, v65
	v_add_f32_e32 v65, v79, v65
	v_pk_mul_f32 v[50:51], v[50:51], v[194:195] op_sel_hi:[1,0]
	s_waitcnt lgkmcnt(0)
	v_mfma_f32_16x16x32_bf16 v[72:75], v[60:63], v[84:87], v[52:55]
	v_mul_f32_e64 v48, v48, v194
	v_mul_f32_e64 v49, v49, v194
	v_pk_mul_f32 v[42:43], v[42:43], v[194:195] op_sel_hi:[1,0]
	v_pk_mul_f32 v[40:41], v[40:41], v[194:195] op_sel_hi:[1,0]
	ds_read_b128 v[52:55], v165 offset:11520
	v_mfma_f32_16x16x32_bf16 v[48:51], v[56:59], v[190:193], v[48:51]
	v_add_f32_e32 v56, v76, v65
	v_add_f32_e32 v65, v77, v56
	ds_read_b128 v[56:59], v165 offset:11584
	v_pk_mul_f32 v[46:47], v[46:47], v[64:65] op_sel_hi:[1,0]
	v_pk_mul_f32 v[44:45], v[44:45], v[64:65] op_sel_hi:[1,0]
	v_mfma_f32_16x16x32_bf16 v[60:63], v[60:63], v[228:231], v[48:51]
	v_mul_f32_e64 v38, v38, v64
	v_mul_f32_e64 v39, v39, v64
	v_pk_mul_f32 v[36:37], v[36:37], v[64:65] op_sel_hi:[1,0]
	v_pk_mul_f32 v[30:31], v[30:31], v[194:195] op_sel_hi:[1,0]
	s_waitcnt lgkmcnt(1)
	v_mfma_f32_16x16x32_bf16 v[44:47], v[52:55], v[68:71], v[44:47]
	v_add_f32_e32 v48, v188, v65
	v_add_f32_e32 v189, v189, v48
	ds_read_b128 v[48:51], v165 offset:13888
	s_waitcnt lgkmcnt(1)
	v_mfma_f32_16x16x32_bf16 v[76:79], v[56:59], v[84:87], v[44:47]
	v_mul_f32_e64 v28, v28, v194
	v_mul_f32_e64 v29, v29, v194
	v_fmac_f32_e32 v189, v187, v64
	v_pk_mul_f32 v[34:35], v[34:35], v[64:65] op_sel_hi:[1,0]
	ds_read_b128 v[44:47], v165 offset:13824
	v_mfma_f32_16x16x32_bf16 v[40:43], v[52:55], v[190:193], v[40:43]
	v_mul_f32_e64 v32, v32, v64
	v_mul_f32_e64 v33, v33, v64
	v_pk_mul_f32 v[26:27], v[26:27], v[194:195] op_sel_hi:[1,0]
	v_pk_mul_f32 v[24:25], v[24:25], v[194:195] op_sel_hi:[1,0]
	s_waitcnt lgkmcnt(0)
	v_mfma_f32_16x16x32_bf16 v[36:39], v[44:47], v[68:71], v[36:39]
	v_mov_b64_e32 v[52:53], v[72:73]
	v_mov_b32_e32 v187, v189
	v_mov_b32_e32 v163, v227
	v_mfma_f32_16x16x32_bf16 v[56:59], v[56:59], v[228:231], v[40:43]
	v_mov_b32_e32 v161, v232
	v_mov_b64_e32 v[54:55], v[74:75]
	s_nop 0
	v_add_f32_e32 v40, v195, v233
	v_add_f32_e32 v40, v234, v40
	v_mfma_f32_16x16x32_bf16 v[80:83], v[48:51], v[84:87], v[36:39]
	v_add_f32_e32 v40, v235, v40
	v_add_f32_e32 v40, v236, v40
	v_add_f32_e32 v40, v237, v40
	ds_read_b128 v[36:39], v226 offset:9216
	v_mfma_f32_16x16x32_bf16 v[28:31], v[44:47], v[190:193], v[28:31]
	v_add_f32_e32 v44, v238, v40
	ds_read_b128 v[40:43], v226 offset:9280
	v_mfma_f32_16x16x32_bf16 v[64:67], v[48:51], v[228:231], v[28:31]
	v_mov_b64_e32 v[48:49], v[60:61]
	v_mov_b64_e32 v[50:51], v[62:63]
	s_nop 2
	v_add_f32_e32 v28, v239, v44
	v_add_f32_e32 v28, v240, v28
	v_add_f32_e32 v44, v241, v28
	s_waitcnt lgkmcnt(1)
	v_mfma_f32_16x16x32_bf16 v[28:31], v[36:39], v[68:71], v[32:35]
	v_mfma_f32_16x16x32_bf16 v[24:27], v[36:39], v[190:193], v[24:27]
	s_nop 1
	v_add_f32_e32 v32, v242, v44
	v_add_f32_e32 v32, v243, v32
	v_add_f32_e32 v32, v244, v32
	s_waitcnt lgkmcnt(0)
	v_mfma_f32_16x16x32_bf16 v[84:87], v[40:43], v[84:87], v[28:31]
	v_mov_b64_e32 v[44:45], v[76:77]
	v_mov_b64_e32 v[36:37], v[80:81]
	v_mov_b64_e32 v[46:47], v[78:79]
	v_mfma_f32_16x16x32_bf16 v[68:71], v[40:43], v[228:231], v[24:27]
	v_add_f32_e32 v28, v245, v32
	v_add_f32_e32 v28, v246, v28
	v_add_f32_e32 v188, v247, v28
	v_fmac_f32_e32 v188, v186, v194
	v_mov_b64_e32 v[32:33], v[84:85]
	v_mov_b64_e32 v[40:41], v[56:57]
	v_mov_b64_e32 v[28:29], v[64:65]
	s_nop 0
	v_mov_b64_e32 v[24:25], v[68:69]
	v_mov_b32_e32 v186, v188
	v_mov_b64_e32 v[38:39], v[82:83]
	v_mov_b64_e32 v[34:35], v[86:87]
	v_mov_b64_e32 v[42:43], v[58:59]
	v_mov_b64_e32 v[30:31], v[66:67]
	v_mov_b64_e32 v[26:27], v[70:71]
	s_andn2_b64 vcc, exec, s[54:55]
	s_cbranch_vccnz .LBB0_1046

; #define BAR_LDS() do { asm volatile("s_waitcnt lgkmcnt(0)" ::: "memory"); __builtin_amdgcn_s_barrier(); asm volatile("" ::: "memory"); } while (0)
; #define DB_GLOAD(SK, SV, kb_) do { SK = *(const v4u*)(kbase + (size_t)((kb_) + srow) * ldk + sch); if (MODE != 0) SV = *(const v4u*)(vbase + (size_t)srow * ldv + (kb_) + sch); } while (0)
; #define DB_LWRITE(SK, SV, buf_) do { LAS unsigned char* nb_ = lds + NSA_TILE0 + (buf_) * NSA_TILE_STRIDE; *(LAS v4u*)((LAS bf16*)nb_ + krow * KT_LD + sch) = SK; if (MODE != 0) *(LAS v4u*)((LAS bf16*)(nb_ + NSA_V_OFF) + srow * KT_LD + sch) = SV; } while (0)
; template <int MODE>
; __device__ __forceinline__ void nsa_soft(f32x4 (&st)[4], const float (&Bl)[16], float cl, bool fast, int keybase, int t, bool sel, float& m2, float& l, f32x4 (&o)[4], float lfin, LAS float* imp, int lane) {
;     ...
;         float ps = 0.f;
; #pragma unroll
;         for (int tau = 0; tau < 4; ++tau)
; #pragma unroll
;             for (int r = 0; r < 4; ++r) { const float p = __builtin_amdgcn_exp2f(st[tau][r] + sh); st[tau][r] = p; ps += p; }
;         l = l * alpha + ps;
; template <int MODE> ...
;     ...
;     for (int s = 0; s < nst; ++s) {
;         const int kb = kb0 + s * 64;
;         if (s + 1 < nst) DB_GLOAD(skA, svA, kb + 64);
;         DB_COMPUTE(kb, s & 1);
;         if (s + 1 < nst) DB_LWRITE(skA, svA, (s + 1) & 1);
;         BAR_LDS();
;     }
.LBB0_1063:
	v_add_f32_e32 v180, 0, v180
	v_add_f32_e32 v180, v181, v180
	v_add_f32_e32 v180, v182, v180
	v_add_f32_e32 v57, v57, v180
	v_add_f32_e32 v57, v183, v57
	v_add_f32_e32 v57, v184, v57
	v_add_f32_e32 v57, v185, v57
	v_add_f32_e32 v57, v59, v57
	v_add_f32_e32 v57, v62, v57
	v_add_f32_e32 v57, v63, v57
	v_add_f32_e32 v57, v60, v57
	v_add_f32_e32 v57, v61, v57
	v_add_f32_e32 v57, v64, v57
	v_add_f32_e32 v57, v65, v57
	v_add_f32_e32 v57, v66, v57
	v_add_f32_e32 v57, v67, v57
	v_fmac_f32_e32 v57, v189, v58
	v_add_f32_e32 v58, v70, v69
	v_add_f32_e32 v58, v71, v58
	v_add_f32_e32 v58, v166, v58
	v_add_f32_e32 v58, v167, v58
	v_add_f32_e32 v58, v168, v58
	v_add_f32_e32 v58, v169, v58
	v_add_f32_e32 v58, v170, v58
	v_add_f32_e32 v58, v171, v58
	v_add_f32_e32 v58, v172, v58
	v_add_f32_e32 v58, v173, v58
	v_add_f32_e32 v58, v174, v58
	v_add_f32_e32 v58, v175, v58
	v_add_f32_e32 v58, v176, v58
	v_add_f32_e32 v58, v177, v58
	s_waitcnt lgkmcnt(0)
	s_barrier
	v_add_f32_e32 v58, v178, v58
	s_add_i32 s5, s5, 64
	s_sub_i32 s16, s16, 64
	v_fmac_f32_e32 v58, v188, v56
	v_add_u32_e32 v187, 64, v187
	v_add_u32_e32 v147, 64, v147
	v_add_u32_e32 v155, 64, v155
	v_add_u32_e32 v161, 64, v161
	s_cmp_lg_u32 s15, s17
	v_add_u32_e32 v186, 64, v186
	s_cbranch_scc0 .LBB0_897
	v_mov_b32_e32 v189, v57
	v_mov_b32_e32 v188, v58
	v_mov_b32_e32 v190, v179
	v_mov_b32_e32 v191, v68
	s_branch .LBB0_1055
